# S5 phase: projection waves wait for the next chunk's global loads behind the per-chunk barrier instead of before it
# speedup vs baseline: 1.0558x; 1.0026x over previous
.LBB0_1091:
	s_add_i32 s40, s40, 1
	s_add_i32 s2, s2, 64
	v_lshl_add_u64 v[120:121], v[120:121], 0, s[34:35]
	s_waitcnt lgkmcnt(0)
	s_barrier
	s_and_b64 vcc, exec, s[28:29]
	s_cbranch_vccz .Ls5T_done_0
	s_cmp_eq_u32 s100, 0
	s_cbranch_scc1 .Ls5T_noperm_0
	s_waitcnt vmcnt(2)
	v_perm_b32 v143, v11, v10, s51
	s_waitcnt vmcnt(0)
	v_perm_b32 v107, v8, v12, s51

.Ls5T_done_0:
	s_cmpk_eq_i32 s2, 0xfc0
	s_cbranch_scc1 .LBB0_1109
.LBB0_1092:
	s_and_b64 vcc, exec, s[28:29]
	s_cbranch_vccz .LBB0_1107
	s_mov_b32 s100, 0
	s_waitcnt vmcnt(0)
	v_mov_b64_e32 v[0:1], v[56:57]
	v_mov_b64_e32 v[4:5], v[52:53]
	s_cmpk_eq_i32 s2, 0xf80
	v_mov_b64_e32 v[2:3], v[58:59]
	v_mov_b64_e32 v[6:7], v[54:55]
	s_cbranch_scc1 .LBB0_1103
	s_cmp_lt_i32 s45, 1
	v_mov_b32_e32 v0, v97
	v_mov_b32_e32 v1, v99
	v_mov_b32_e32 v2, v101
	v_mov_b32_e32 v3, v103
	s_cbranch_scc1 .LBB0_1099
	s_cmp_lg_u32 s45, 1
	s_mov_b64 s[38:39], -1
	s_cbranch_scc0 .LBB0_1097
	s_mov_b64 s[38:39], 0

.LBB0_1103:
	s_cmpk_eq_i32 s2, 0xffc0
	s_cbranch_scc1 .LBB0_1106
	s_andn2_b64 vcc, exec, s[24:25]
	s_cbranch_vccnz .LBB0_1106
	s_and_b32 s38, s2, 64
	s_mulk_i32 s38, 0x110
	v_add_u32_e32 v66, s38, v125
	ds_read_b128 v[8:11], v66
	ds_read_b128 v[12:15], v66 offset:64
	ds_read_b128 v[148:151], v66 offset:128
	ds_read_b128 v[152:155], v66 offset:192
	v_lshlrev_b32_e32 v66, 16, v143
	s_waitcnt lgkmcnt(3)
	v_mfma_f32_16x16x32_bf16 v[8:11], v[8:11], v[48:51], 0
	v_and_b32_e32 v143, 0xffff0000, v143
	v_lshlrev_b32_e32 v147, 16, v107
	v_lshl_add_u64 v[156:157], v[116:117], 0, s[2:3]
	s_waitcnt lgkmcnt(2)
	v_mfma_f32_16x16x32_bf16 v[8:11], v[12:15], v[44:47], v[8:11]
	v_lshlrev_b64 v[12:13], 10, v[156:157]
	v_lshl_add_u64 v[14:15], v[110:111], 0, v[12:13]
	s_waitcnt lgkmcnt(1)
	v_mfma_f32_16x16x32_bf16 v[8:11], v[148:151], v[40:43], v[8:11]
	v_or_b32_e32 v148, 0x400, v12
	v_mov_b32_e32 v149, v13
	s_waitcnt lgkmcnt(0)
	v_mfma_f32_16x16x32_bf16 v[8:11], v[152:155], v[36:39], v[8:11]
	s_nop 7
	v_fma_f32 v8, v142, v66, v8
	v_mul_f32_e32 v66, 0x3d372713, v8
	v_fma_f32 v9, v142, v143, v9
	v_mul_f32_e32 v66, v8, v66
	v_mul_f32_e32 v143, 0x3d372713, v9
	v_fma_f32 v66, v8, v66, v8
	v_mul_f32_e32 v143, v9, v143
	v_mul_f32_e32 v66, 0xbfcc422a, v66
	v_fma_f32 v143, v9, v143, v9
	v_mul_f32_e32 v66, 0x3fb8aa3b, v66
	v_mul_f32_e32 v143, 0xbfcc422a, v143
	v_exp_f32_e32 v66, v66
	v_mul_f32_e32 v143, 0x3fb8aa3b, v143
	v_exp_f32_e32 v143, v143
	v_fma_f32 v10, v142, v147, v10
	v_add_f32_e32 v66, 1.0, v66
	v_rcp_f32_e32 v66, v66
	v_add_f32_e32 v143, 1.0, v143
	v_mul_f32_e32 v147, 0x3d372713, v10
	v_rcp_f32_e32 v143, v143
	v_mul_f32_e32 v147, v10, v147
	v_fma_f32 v147, v10, v147, v10
	v_mul_f32_e32 v8, v8, v66
	v_mul_f32_e32 v147, 0xbfcc422a, v147
	v_cvt_pk_bf16_f32 v8, v8, s0
	v_mul_f32_e32 v9, v9, v143
	global_store_short v[14:15], v8, off
	v_mul_f32_e32 v8, 0x3fb8aa3b, v147
	v_cvt_pk_bf16_f32 v66, v9, s0
	v_exp_f32_e32 v14, v8
	v_lshl_add_u64 v[8:9], v[110:111], 0, v[148:149]
	global_store_short v[8:9], v66, off
	v_and_b32_e32 v9, 0xffff0000, v107
	v_fmac_f32_e32 v11, v142, v9
	v_mul_f32_e32 v9, 0x3d372713, v11
	v_mul_f32_e32 v9, v11, v9
	v_fma_f32 v9, v11, v9, v11
	v_mul_f32_e32 v9, 0xbfcc422a, v9
	v_mul_f32_e32 v9, 0x3fb8aa3b, v9
	v_exp_f32_e32 v9, v9
	v_add_f32_e32 v8, 1.0, v14
	v_rcp_f32_e32 v8, v8
	v_add_f32_e32 v9, 1.0, v9
	v_rcp_f32_e32 v14, v9
	v_mul_f32_e32 v8, v10, v8
	v_cvt_pk_bf16_f32 v10, v8, s0
	v_or_b32_e32 v8, 0x800, v12
	v_mov_b32_e32 v9, v13
	v_lshl_add_u64 v[8:9], v[110:111], 0, v[8:9]
	global_store_short v[8:9], v10, off
	v_mul_f32_e32 v8, v11, v14
	v_or_b32_e32 v12, 0xc00, v12
	v_cvt_pk_bf16_f32 v10, v8, s0
	v_lshl_add_u64 v[8:9], v[110:111], 0, v[12:13]
	global_store_short v[8:9], v10, off
	v_lshl_add_u64 v[8:9], v[120:121], 0, s[30:31]
	v_or_b32_e32 v12, 0x1000, v8
	v_mov_b32_e32 v13, v9
	v_or_b32_e32 v14, 0x2000, v8
	v_or_b32_e32 v8, 0x3000, v8
	v_lshl_add_u64 v[10:11], v[112:113], 0, v[120:121]
	v_lshl_add_u64 v[12:13], v[118:119], 0, v[12:13]
	v_mov_b32_e32 v15, v9
	v_lshl_add_u64 v[8:9], v[118:119], 0, v[8:9]
	v_lshl_add_u64 v[14:15], v[118:119], 0, v[14:15]
	global_load_ushort v10, v[10:11], off
	s_nop 0
	global_load_ushort v11, v[12:13], off
	s_nop 0
	global_load_ushort v12, v[14:15], off
	s_nop 0
	global_load_ushort v8, v[8:9], off
	s_mov_b32 s100, 1

.LBB0_1107:
	s_cbranch_execnz .LBB0_1090
.LBB0_1108:
	s_branch .LBB0_1091
.LBB0_1109:
	s_andn2_b64 vcc, exec, s[26:27]
	s_cbranch_vccnz .LBB0_1050
	ds_read_b128 v[0:3], v133
	ds_read_b128 v[4:7], v133 offset:64
	ds_read_b128 v[8:11], v133 offset:128
	ds_read_b128 v[12:15], v133 offset:192
	s_waitcnt lgkmcnt(3)
	v_mfma_f32_16x16x32_bf16 v[0:3], v[0:3], v[48:51], 0
	v_mov_b32_e32 v49, s37
	v_or_b32_e32 v48, s36, v88
	s_waitcnt lgkmcnt(2)
	v_mfma_f32_16x16x32_bf16 v[0:3], v[4:7], v[44:47], v[0:3]
	v_lshlrev_b32_e32 v44, 16, v143
	v_and_b32_e32 v45, 0xffff0000, v143
	v_lshlrev_b32_e32 v46, 16, v107
	s_waitcnt lgkmcnt(1)
	v_mfma_f32_16x16x32_bf16 v[0:3], v[8:11], v[40:43], v[0:3]
	v_lshlrev_b64 v[4:5], 10, v[48:49]
	v_lshl_add_u64 v[6:7], v[110:111], 0, v[4:5]
	v_or_b32_e32 v8, 0x400, v4
	s_waitcnt lgkmcnt(0)
	v_mfma_f32_16x16x32_bf16 v[0:3], v[12:15], v[36:39], v[0:3]
	s_nop 7
	v_fma_f32 v0, v142, v44, v0
	v_mul_f32_e32 v9, 0x3d372713, v0
	v_mul_f32_e32 v9, v0, v9
	v_fma_f32 v1, v142, v45, v1
	v_fma_f32 v9, v0, v9, v0
	v_mul_f32_e32 v10, 0x3d372713, v1
	v_mul_f32_e32 v9, 0xbfcc422a, v9
	v_mul_f32_e32 v10, v1, v10
	v_mul_f32_e32 v9, 0x3fb8aa3b, v9
	v_fma_f32 v10, v1, v10, v1
	v_exp_f32_e32 v9, v9
	v_mul_f32_e32 v10, 0xbfcc422a, v10
	v_mul_f32_e32 v10, 0x3fb8aa3b, v10
	v_exp_f32_e32 v10, v10
	v_add_f32_e32 v9, 1.0, v9
	v_rcp_f32_e32 v9, v9
	v_fma_f32 v2, v142, v46, v2
	v_add_f32_e32 v10, 1.0, v10
	v_mul_f32_e32 v11, 0x3d372713, v2
	v_rcp_f32_e32 v10, v10
	v_mul_f32_e32 v11, v2, v11
	v_mul_f32_e32 v0, v0, v9
	v_fma_f32 v11, v2, v11, v2
	v_cvt_pk_bf16_f32 v0, v0, s0
	global_store_short v[6:7], v0, off
	v_mul_f32_e32 v0, 0xbfcc422a, v11
	v_mul_f32_e32 v1, v1, v10
	v_mul_f32_e32 v0, 0x3fb8aa3b, v0
	v_mov_b32_e32 v9, v5
	v_cvt_pk_bf16_f32 v10, v1, s0
	v_exp_f32_e32 v6, v0
	v_lshl_add_u64 v[0:1], v[110:111], 0, v[8:9]
	global_store_short v[0:1], v10, off
	v_and_b32_e32 v1, 0xffff0000, v107
	v_fmac_f32_e32 v3, v142, v1
	v_mul_f32_e32 v1, 0x3d372713, v3
	v_mul_f32_e32 v1, v3, v1
	v_fma_f32 v1, v3, v1, v3
	v_mul_f32_e32 v1, 0xbfcc422a, v1
	v_mul_f32_e32 v1, 0x3fb8aa3b, v1
	v_exp_f32_e32 v1, v1
	v_add_f32_e32 v0, 1.0, v6
	v_rcp_f32_e32 v0, v0
	v_add_f32_e32 v1, 1.0, v1
	v_rcp_f32_e32 v6, v1
	v_mul_f32_e32 v0, v2, v0
	v_cvt_pk_bf16_f32 v2, v0, s0
	v_or_b32_e32 v0, 0x800, v4
	v_mov_b32_e32 v1, v5
	v_lshl_add_u64 v[0:1], v[110:111], 0, v[0:1]
	global_store_short v[0:1], v2, off
	v_mul_f32_e32 v0, v3, v6
	v_or_b32_e32 v4, 0xc00, v4
	v_cvt_pk_bf16_f32 v2, v0, s0
	v_lshl_add_u64 v[0:1], v[110:111], 0, v[4:5]
	global_store_short v[0:1], v2, off
	s_branch .LBB0_1050

.LBB0_2587:
	s_cbranch_execnz .LBB0_2570
.LBB0_2588:
	s_branch .LBB0_2571
.LBB0_2589:
	s_andn2_b64 vcc, exec, s[26:27]
	s_cbranch_vccnz .LBB0_2530
	ds_read_b128 v[0:3], v133
	ds_read_b128 v[4:7], v133 offset:64
	ds_read_b128 v[8:11], v133 offset:128
	ds_read_b128 v[12:15], v133 offset:192
	s_waitcnt lgkmcnt(3)
	v_mfma_f32_16x16x32_bf16 v[0:3], v[0:3], v[48:51], 0
	v_mov_b32_e32 v49, s37
	v_or_b32_e32 v48, s36, v88
	s_waitcnt lgkmcnt(2)
	v_mfma_f32_16x16x32_bf16 v[0:3], v[4:7], v[44:47], v[0:3]
	v_lshlrev_b32_e32 v44, 16, v143
	v_and_b32_e32 v45, 0xffff0000, v143
	v_lshlrev_b32_e32 v46, 16, v107
	s_waitcnt lgkmcnt(1)
	v_mfma_f32_16x16x32_bf16 v[0:3], v[8:11], v[40:43], v[0:3]
	v_lshlrev_b64 v[4:5], 10, v[48:49]
	v_lshl_add_u64 v[6:7], v[110:111], 0, v[4:5]
	v_or_b32_e32 v8, 0x400, v4
	s_waitcnt lgkmcnt(0)
	v_mfma_f32_16x16x32_bf16 v[0:3], v[12:15], v[36:39], v[0:3]
	s_nop 7
	v_fma_f32 v0, v142, v44, v0
	v_mul_f32_e32 v9, 0x3d372713, v0
	v_mul_f32_e32 v9, v0, v9
	v_fma_f32 v1, v142, v45, v1
	v_fma_f32 v9, v0, v9, v0
	v_mul_f32_e32 v10, 0x3d372713, v1
	v_mul_f32_e32 v9, 0xbfcc422a, v9
	v_mul_f32_e32 v10, v1, v10
	v_mul_f32_e32 v9, 0x3fb8aa3b, v9
	v_fma_f32 v10, v1, v10, v1
	v_exp_f32_e32 v9, v9
	v_mul_f32_e32 v10, 0xbfcc422a, v10
	v_mul_f32_e32 v10, 0x3fb8aa3b, v10
	v_exp_f32_e32 v10, v10
	v_add_f32_e32 v9, 1.0, v9
	v_rcp_f32_e32 v9, v9
	v_fma_f32 v2, v142, v46, v2
	v_add_f32_e32 v10, 1.0, v10
	v_mul_f32_e32 v11, 0x3d372713, v2
	v_rcp_f32_e32 v10, v10
	v_mul_f32_e32 v11, v2, v11
	v_mul_f32_e32 v0, v0, v9
	v_fma_f32 v11, v2, v11, v2
	v_cvt_pk_bf16_f32 v0, v0, s0
	global_store_short v[6:7], v0, off
	v_mul_f32_e32 v0, 0xbfcc422a, v11
	v_mul_f32_e32 v1, v1, v10
	v_mul_f32_e32 v0, 0x3fb8aa3b, v0
	v_mov_b32_e32 v9, v5
	v_cvt_pk_bf16_f32 v10, v1, s0
	v_exp_f32_e32 v6, v0
	v_lshl_add_u64 v[0:1], v[110:111], 0, v[8:9]
	global_store_short v[0:1], v10, off
	v_and_b32_e32 v1, 0xffff0000, v107
	v_fmac_f32_e32 v3, v142, v1
	v_mul_f32_e32 v1, 0x3d372713, v3
	v_mul_f32_e32 v1, v3, v1
	v_fma_f32 v1, v3, v1, v3
	v_mul_f32_e32 v1, 0xbfcc422a, v1
	v_mul_f32_e32 v1, 0x3fb8aa3b, v1
	v_exp_f32_e32 v1, v1
	v_add_f32_e32 v0, 1.0, v6
	v_rcp_f32_e32 v0, v0
	v_add_f32_e32 v1, 1.0, v1
	v_rcp_f32_e32 v6, v1
	v_mul_f32_e32 v0, v2, v0
	v_cvt_pk_bf16_f32 v2, v0, s0
	v_or_b32_e32 v0, 0x800, v4
	v_mov_b32_e32 v1, v5
	v_lshl_add_u64 v[0:1], v[110:111], 0, v[0:1]
	global_store_short v[0:1], v2, off
	v_mul_f32_e32 v0, v3, v6
	v_or_b32_e32 v4, 0xc00, v4
	v_cvt_pk_bf16_f32 v2, v0, s0
	v_lshl_add_u64 v[0:1], v[110:111], 0, v[4:5]
	global_store_short v[0:1], v2, off
	s_branch .LBB0_2530
